# QK ring: one lgkmcnt wait per k-step (both K fragments) instead of one per MFMA (8 waits instead of 16 per tile)
# baseline (speedup 1.0000x reference)
.LBB0_513:
	s_lshl_b32 s4, s76, 14
	v_add3_u32 v236, s4, v221, v220
	ds_read_b128 v[192:195], v236
	ds_read_b128 v[196:199], v236 offset:8192
	v_add3_u32 v236, s4, v222, v220
	ds_read_b128 v[200:203], v236
	ds_read_b128 v[204:207], v236 offset:8192
	v_add3_u32 v236, s4, v223, v220
	ds_read_b128 v[240:243], v236
	ds_read_b128 v[244:247], v236 offset:8192
	v_add3_u32 v236, s4, v224, v220
	ds_read_b128 v[248:251], v236
	ds_read_b128 v[252:255], v236 offset:8192
	s_waitcnt lgkmcnt(6)
	v_mfma_f32_32x32x16_bf16 v[144:159], v[192:195], v[160:163], 0
	v_mfma_f32_32x32x16_bf16 v[128:143], v[196:199], v[160:163], 0
	v_add3_u32 v236, s4, v225, v220
	ds_read_b128 v[192:195], v236
	ds_read_b128 v[196:199], v236 offset:8192
	s_waitcnt lgkmcnt(6)
	v_mfma_f32_32x32x16_bf16 v[144:159], v[200:203], v[164:167], v[144:159]
	v_mfma_f32_32x32x16_bf16 v[128:143], v[204:207], v[164:167], v[128:143]
	v_add3_u32 v236, s4, v227, v220
	ds_read_b128 v[200:203], v236
	ds_read_b128 v[204:207], v236 offset:8192
	s_waitcnt lgkmcnt(6)
	v_mfma_f32_32x32x16_bf16 v[144:159], v[240:243], v[168:171], v[144:159]
	v_mfma_f32_32x32x16_bf16 v[128:143], v[244:247], v[168:171], v[128:143]
	v_add3_u32 v236, s4, v228, v220
	ds_read_b128 v[240:243], v236
	ds_read_b128 v[244:247], v236 offset:8192
	s_waitcnt lgkmcnt(6)
	v_mfma_f32_32x32x16_bf16 v[144:159], v[248:251], v[172:175], v[144:159]
	v_mfma_f32_32x32x16_bf16 v[128:143], v[252:255], v[172:175], v[128:143]
	v_add3_u32 v236, s4, v229, v220
	ds_read_b128 v[248:251], v236
	ds_read_b128 v[252:255], v236 offset:8192
	s_waitcnt lgkmcnt(6)
	v_mfma_f32_32x32x16_bf16 v[144:159], v[192:195], v[176:179], v[144:159]
	v_mfma_f32_32x32x16_bf16 v[128:143], v[196:199], v[176:179], v[128:143]
	s_waitcnt lgkmcnt(4)
	v_mfma_f32_32x32x16_bf16 v[144:159], v[200:203], v[180:183], v[144:159]
	v_mfma_f32_32x32x16_bf16 v[128:143], v[204:207], v[180:183], v[128:143]
	s_waitcnt lgkmcnt(2)
	v_mfma_f32_32x32x16_bf16 v[144:159], v[240:243], v[184:187], v[144:159]
	v_mfma_f32_32x32x16_bf16 v[128:143], v[244:247], v[184:187], v[128:143]
	s_waitcnt lgkmcnt(0)
	v_mfma_f32_32x32x16_bf16 v[144:159], v[248:251], v[188:191], v[144:159]
	v_mfma_f32_32x32x16_bf16 v[128:143], v[252:255], v[188:191], v[128:143]
	s_nop 9
	v_max_f32_e32 v192, v144, v145
	v_max3_f32 v192, v192, v146, v147
	v_max3_f32 v192, v192, v148, v149
	v_max3_f32 v192, v192, v150, v151
	v_max3_f32 v192, v192, v152, v153
	v_max3_f32 v192, v192, v154, v155
	v_max3_f32 v192, v192, v156, v157
	v_max3_f32 v192, v192, v158, v159
	v_max3_f32 v192, v192, v128, v129
	v_max3_f32 v192, v192, v130, v131
	v_max3_f32 v192, v192, v132, v133
	v_max3_f32 v192, v192, v134, v135
	v_max3_f32 v192, v192, v136, v137
	v_max3_f32 v192, v192, v138, v139
	v_max3_f32 v192, v192, v140, v141
	v_max3_f32 v192, v192, v142, v143
	v_mov_b32_e32 v193, v192
	s_nop 1
	v_permlane32_swap_b32_e32 v192, v193
	v_max_f32_e32 v192, v192, v193
	v_sub_f32_e32 v193, v192, v231
	v_cmp_ge_f32_e32 vcc, s38, v193
	s_cmp_eq_u64 vcc, exec
	s_cbranch_scc1 .LBB0_517
	v_max_f32_e32 v234, v231, v192
	v_sub_f32_e32 v192, v231, v234
	v_mul_f32_e32 v192, 0x3e0293ee, v192
	v_exp_f32_e32 v233, v192
	v_mov_b32_e32 v231, v234
	v_mul_f32_e32 v237, 0xbe0293ee, v234
	v_mul_f32_e32 v232, v232, v233
	s_and_saveexec_b64 s[24:25], s[0:1]
	ds_write_b32 v226, v233 offset:128
	s_or_b64 exec, exec, s[24:25]
	s_waitcnt lgkmcnt(0)
	v_add_u32_e32 v192, s21, v210
	ds_read_b128 v[204:207], v192 offset:224
	ds_read_b128 v[200:203], v192 offset:192
	ds_read_b128 v[196:199], v192 offset:160
	ds_read_b128 v[192:195], v192 offset:128
	s_waitcnt lgkmcnt(3)
	v_pk_mul_f32 v[12:13], v[12:13], v[204:205]
	s_waitcnt lgkmcnt(2)
	v_pk_mul_f32 v[8:9], v[8:9], v[200:201]
	s_waitcnt lgkmcnt(1)
	v_pk_mul_f32 v[4:5], v[4:5], v[196:197]
	v_pk_mul_f32 v[14:15], v[14:15], v[206:207]
	v_pk_mul_f32 v[10:11], v[10:11], v[202:203]
	v_pk_mul_f32 v[6:7], v[6:7], v[198:199]
	s_waitcnt lgkmcnt(0)
	v_pk_mul_f32 v[2:3], v[2:3], v[194:195]
	v_pk_mul_f32 v[0:1], v[0:1], v[192:193]
	v_pk_mul_f32 v[124:125], v[124:125], v[204:205]
	v_pk_mul_f32 v[120:121], v[120:121], v[200:201]
	v_pk_mul_f32 v[116:117], v[116:117], v[196:197]
	v_pk_mul_f32 v[126:127], v[126:127], v[206:207]
	v_pk_mul_f32 v[122:123], v[122:123], v[202:203]
	v_pk_mul_f32 v[118:119], v[118:119], v[198:199]
	v_pk_mul_f32 v[114:115], v[114:115], v[194:195]
	v_pk_mul_f32 v[112:113], v[112:113], v[192:193]
	v_pk_mul_f32 v[108:109], v[108:109], v[204:205]
	v_pk_mul_f32 v[104:105], v[104:105], v[200:201]
	v_pk_mul_f32 v[100:101], v[100:101], v[196:197]
	v_pk_mul_f32 v[110:111], v[110:111], v[206:207]
	v_pk_mul_f32 v[106:107], v[106:107], v[202:203]
	v_pk_mul_f32 v[102:103], v[102:103], v[198:199]
	v_pk_mul_f32 v[98:99], v[98:99], v[194:195]
	v_pk_mul_f32 v[96:97], v[96:97], v[192:193]
	v_pk_mul_f32 v[92:93], v[92:93], v[204:205]
	v_pk_mul_f32 v[88:89], v[88:89], v[200:201]
	v_pk_mul_f32 v[84:85], v[84:85], v[196:197]
	v_pk_mul_f32 v[94:95], v[94:95], v[206:207]
	v_pk_mul_f32 v[90:91], v[90:91], v[202:203]
	v_pk_mul_f32 v[86:87], v[86:87], v[198:199]
	v_pk_mul_f32 v[82:83], v[82:83], v[194:195]
	v_pk_mul_f32 v[80:81], v[80:81], v[192:193]
	v_pk_mul_f32 v[76:77], v[76:77], v[204:205]
	v_pk_mul_f32 v[72:73], v[72:73], v[200:201]
	v_pk_mul_f32 v[68:69], v[68:69], v[196:197]
	v_pk_mul_f32 v[78:79], v[78:79], v[206:207]
	v_pk_mul_f32 v[74:75], v[74:75], v[202:203]
	v_pk_mul_f32 v[70:71], v[70:71], v[198:199]
	v_pk_mul_f32 v[66:67], v[66:67], v[194:195]
	v_pk_mul_f32 v[64:65], v[64:65], v[192:193]
	v_pk_mul_f32 v[60:61], v[60:61], v[204:205]
	v_pk_mul_f32 v[56:57], v[56:57], v[200:201]
	v_pk_mul_f32 v[52:53], v[52:53], v[196:197]
	v_pk_mul_f32 v[62:63], v[62:63], v[206:207]
	v_pk_mul_f32 v[58:59], v[58:59], v[202:203]
	v_pk_mul_f32 v[54:55], v[54:55], v[198:199]
	v_pk_mul_f32 v[50:51], v[50:51], v[194:195]
	v_pk_mul_f32 v[48:49], v[48:49], v[192:193]
	v_pk_mul_f32 v[44:45], v[44:45], v[204:205]
	v_pk_mul_f32 v[40:41], v[40:41], v[200:201]
	v_pk_mul_f32 v[36:37], v[36:37], v[196:197]
	v_pk_mul_f32 v[46:47], v[46:47], v[206:207]
	v_pk_mul_f32 v[42:43], v[42:43], v[202:203]
	v_pk_mul_f32 v[38:39], v[38:39], v[198:199]
	v_pk_mul_f32 v[34:35], v[34:35], v[194:195]
	v_pk_mul_f32 v[32:33], v[32:33], v[192:193]
	v_pk_mul_f32 v[28:29], v[28:29], v[204:205]
	v_pk_mul_f32 v[24:25], v[24:25], v[200:201]
	v_pk_mul_f32 v[20:21], v[20:21], v[196:197]
	v_pk_mul_f32 v[30:31], v[30:31], v[206:207]
	v_pk_mul_f32 v[26:27], v[26:27], v[202:203]
	v_pk_mul_f32 v[22:23], v[22:23], v[198:199]
	v_pk_mul_f32 v[18:19], v[18:19], v[194:195]
	v_pk_mul_f32 v[16:17], v[16:17], v[192:193]

.LBB0_906:
	s_lshl_b32 s4, s80, 14
	v_add3_u32 v236, s4, v221, v220
	ds_read_b128 v[192:195], v236
	ds_read_b128 v[196:199], v236 offset:8192
	v_add3_u32 v236, s4, v222, v220
	ds_read_b128 v[200:203], v236
	ds_read_b128 v[204:207], v236 offset:8192
	v_add3_u32 v236, s4, v223, v220
	ds_read_b128 v[240:243], v236
	ds_read_b128 v[244:247], v236 offset:8192
	v_add3_u32 v236, s4, v225, v220
	ds_read_b128 v[248:251], v236
	ds_read_b128 v[252:255], v236 offset:8192
	s_waitcnt lgkmcnt(6)
	v_mfma_f32_32x32x16_bf16 v[144:159], v[192:195], v[160:163], 0
	v_mfma_f32_32x32x16_bf16 v[128:143], v[196:199], v[160:163], 0
	v_add3_u32 v236, s4, v226, v220
	ds_read_b128 v[192:195], v236
	ds_read_b128 v[196:199], v236 offset:8192
	s_waitcnt lgkmcnt(6)
	v_mfma_f32_32x32x16_bf16 v[144:159], v[200:203], v[164:167], v[144:159]
	v_mfma_f32_32x32x16_bf16 v[128:143], v[204:207], v[164:167], v[128:143]
	v_add3_u32 v236, s4, v227, v220
	ds_read_b128 v[200:203], v236
	ds_read_b128 v[204:207], v236 offset:8192
	s_waitcnt lgkmcnt(6)
	v_mfma_f32_32x32x16_bf16 v[144:159], v[240:243], v[168:171], v[144:159]
	v_mfma_f32_32x32x16_bf16 v[128:143], v[244:247], v[168:171], v[128:143]
	v_add3_u32 v236, s4, v228, v220
	ds_read_b128 v[240:243], v236
	ds_read_b128 v[244:247], v236 offset:8192
	s_waitcnt lgkmcnt(6)
	v_mfma_f32_32x32x16_bf16 v[144:159], v[248:251], v[172:175], v[144:159]
	v_mfma_f32_32x32x16_bf16 v[128:143], v[252:255], v[172:175], v[128:143]
	v_add3_u32 v236, s4, v229, v220
	ds_read_b128 v[248:251], v236
	ds_read_b128 v[252:255], v236 offset:8192
	s_waitcnt lgkmcnt(6)
	v_mfma_f32_32x32x16_bf16 v[144:159], v[192:195], v[176:179], v[144:159]
	v_mfma_f32_32x32x16_bf16 v[128:143], v[196:199], v[176:179], v[128:143]
	s_waitcnt lgkmcnt(4)
	v_mfma_f32_32x32x16_bf16 v[144:159], v[200:203], v[180:183], v[144:159]
	v_mfma_f32_32x32x16_bf16 v[128:143], v[204:207], v[180:183], v[128:143]
	s_waitcnt lgkmcnt(2)
	v_mfma_f32_32x32x16_bf16 v[144:159], v[240:243], v[184:187], v[144:159]
	v_mfma_f32_32x32x16_bf16 v[128:143], v[244:247], v[184:187], v[128:143]
	s_waitcnt lgkmcnt(0)
	v_mfma_f32_32x32x16_bf16 v[144:159], v[248:251], v[188:191], v[144:159]
	v_mfma_f32_32x32x16_bf16 v[128:143], v[252:255], v[188:191], v[128:143]
	v_max_f32_e32 v194, v231, v231
	s_nop 9
	v_max_f32_e32 v192, v144, v145
	v_max3_f32 v192, v192, v146, v147
	v_max3_f32 v192, v192, v148, v149
	v_max3_f32 v192, v192, v150, v151
	v_max3_f32 v192, v192, v152, v153
	v_max3_f32 v192, v192, v154, v155
	v_max3_f32 v192, v192, v156, v157
	v_max3_f32 v192, v192, v158, v159
	v_max3_f32 v192, v192, v128, v129
	v_max3_f32 v192, v192, v130, v131
	v_max3_f32 v192, v192, v132, v133
	v_max3_f32 v192, v192, v134, v135
	v_max3_f32 v192, v192, v136, v137
	v_max3_f32 v192, v192, v138, v139
	v_max3_f32 v192, v192, v140, v141
	v_max3_f32 v192, v192, v142, v143
	v_mov_b32_e32 v193, v192
	s_nop 1
	v_permlane32_swap_b32_e32 v192, v193
	v_max_f32_e32 v192, v192, v193
	v_sub_f32_e32 v193, v192, v231
	v_cmp_ge_f32_e32 vcc, s42, v193
	s_cmp_eq_u64 vcc, exec
	s_cbranch_scc1 .LBB0_910
	v_max_f32_e32 v234, v194, v192
	v_sub_f32_e32 v192, v231, v234
	v_mul_f32_e32 v192, 0x3e0293ee, v192
	v_exp_f32_e32 v233, v192
	v_mov_b32_e32 v231, v234
	v_mul_f32_e32 v237, 0xbe0293ee, v234
	v_mul_f32_e32 v232, v232, v233
	s_and_saveexec_b64 s[24:25], s[0:1]
	ds_write_b32 v224, v233 offset:128
	s_or_b64 exec, exec, s[24:25]
	s_waitcnt lgkmcnt(0)
	v_add_u32_e32 v192, s21, v210
	ds_read_b128 v[204:207], v192 offset:224
	ds_read_b128 v[200:203], v192 offset:192
	ds_read_b128 v[196:199], v192 offset:160
	ds_read_b128 v[192:195], v192 offset:128
	s_waitcnt lgkmcnt(3)
	v_pk_mul_f32 v[12:13], v[12:13], v[204:205]
	s_waitcnt lgkmcnt(2)
	v_pk_mul_f32 v[8:9], v[8:9], v[200:201]
	s_waitcnt lgkmcnt(1)
	v_pk_mul_f32 v[4:5], v[4:5], v[196:197]
	v_pk_mul_f32 v[14:15], v[14:15], v[206:207]
	v_pk_mul_f32 v[10:11], v[10:11], v[202:203]
	v_pk_mul_f32 v[6:7], v[6:7], v[198:199]
	s_waitcnt lgkmcnt(0)
	v_pk_mul_f32 v[2:3], v[2:3], v[194:195]
	v_pk_mul_f32 v[0:1], v[0:1], v[192:193]
	v_pk_mul_f32 v[124:125], v[124:125], v[204:205]
	v_pk_mul_f32 v[120:121], v[120:121], v[200:201]
	v_pk_mul_f32 v[116:117], v[116:117], v[196:197]
	v_pk_mul_f32 v[126:127], v[126:127], v[206:207]
	v_pk_mul_f32 v[122:123], v[122:123], v[202:203]
	v_pk_mul_f32 v[118:119], v[118:119], v[198:199]
	v_pk_mul_f32 v[114:115], v[114:115], v[194:195]
	v_pk_mul_f32 v[112:113], v[112:113], v[192:193]
	v_pk_mul_f32 v[108:109], v[108:109], v[204:205]
	v_pk_mul_f32 v[104:105], v[104:105], v[200:201]
	v_pk_mul_f32 v[100:101], v[100:101], v[196:197]
	v_pk_mul_f32 v[110:111], v[110:111], v[206:207]
	v_pk_mul_f32 v[106:107], v[106:107], v[202:203]
	v_pk_mul_f32 v[102:103], v[102:103], v[198:199]
	v_pk_mul_f32 v[98:99], v[98:99], v[194:195]
	v_pk_mul_f32 v[96:97], v[96:97], v[192:193]
	v_pk_mul_f32 v[92:93], v[92:93], v[204:205]
	v_pk_mul_f32 v[88:89], v[88:89], v[200:201]
	v_pk_mul_f32 v[84:85], v[84:85], v[196:197]
	v_pk_mul_f32 v[94:95], v[94:95], v[206:207]
	v_pk_mul_f32 v[90:91], v[90:91], v[202:203]
	v_pk_mul_f32 v[86:87], v[86:87], v[198:199]
	v_pk_mul_f32 v[82:83], v[82:83], v[194:195]
	v_pk_mul_f32 v[80:81], v[80:81], v[192:193]
	v_pk_mul_f32 v[76:77], v[76:77], v[204:205]
	v_pk_mul_f32 v[72:73], v[72:73], v[200:201]
	v_pk_mul_f32 v[68:69], v[68:69], v[196:197]
	v_pk_mul_f32 v[78:79], v[78:79], v[206:207]
	v_pk_mul_f32 v[74:75], v[74:75], v[202:203]
	v_pk_mul_f32 v[70:71], v[70:71], v[198:199]
	v_pk_mul_f32 v[66:67], v[66:67], v[194:195]
	v_pk_mul_f32 v[64:65], v[64:65], v[192:193]
	v_pk_mul_f32 v[60:61], v[60:61], v[204:205]
	v_pk_mul_f32 v[56:57], v[56:57], v[200:201]
	v_pk_mul_f32 v[52:53], v[52:53], v[196:197]
	v_pk_mul_f32 v[62:63], v[62:63], v[206:207]
	v_pk_mul_f32 v[58:59], v[58:59], v[202:203]
	v_pk_mul_f32 v[54:55], v[54:55], v[198:199]
	v_pk_mul_f32 v[50:51], v[50:51], v[194:195]
	v_pk_mul_f32 v[48:49], v[48:49], v[192:193]
	v_pk_mul_f32 v[44:45], v[44:45], v[204:205]
	v_pk_mul_f32 v[40:41], v[40:41], v[200:201]
	v_pk_mul_f32 v[36:37], v[36:37], v[196:197]
	v_pk_mul_f32 v[46:47], v[46:47], v[206:207]
	v_pk_mul_f32 v[42:43], v[42:43], v[202:203]
	v_pk_mul_f32 v[38:39], v[38:39], v[198:199]
	v_pk_mul_f32 v[34:35], v[34:35], v[194:195]
	v_pk_mul_f32 v[32:33], v[32:33], v[192:193]
	v_pk_mul_f32 v[28:29], v[28:29], v[204:205]
	v_pk_mul_f32 v[24:25], v[24:25], v[200:201]
	v_pk_mul_f32 v[20:21], v[20:21], v[196:197]
	v_pk_mul_f32 v[30:31], v[30:31], v[206:207]
	v_pk_mul_f32 v[26:27], v[26:27], v[202:203]
	v_pk_mul_f32 v[22:23], v[22:23], v[198:199]
	v_pk_mul_f32 v[18:19], v[18:19], v[194:195]
	v_pk_mul_f32 v[16:17], v[16:17], v[192:193]
